# P1 deferred conversion: one copy of the loop (first/stride/bound in registers): pass 1 all WGs items [3584,7680) + rope table, pass 2 one-unit-fewer WGs items [0,3584); second loop copy deleted
# speedup vs baseline: 1.0082x; 1.0042x over previous
; __device__ __forceinline__ void p0_deferred(const Ptrs& P, LAS unsigned char* lds, int gw, int NGW, int wave, int lane) {
;     ...
;     tr_loop([&](int it) {
;         int r = it;
;         if (r < I_D) return TrD{P.w1d, P.W1D, nullptr, DFF, D, 0, r}; r -= I_D;
;         if (r < I_IN) return TrD{P.win, P.WIN, P.gma, D, INW, 3, r}; r -= I_IN;
;         if (r < I_OUT) return TrD{P.wout, P.WOUT, nullptr, D, D, 0, r}; r -= I_OUT;
;         if (r < I_GU) return TrD{P.w2g, P.W2GU, P.g2a, D, DFF, 1, r}; r -= I_GU;
;         if (r < I_GU) return TrD{P.w2u, P.W2GU, P.g2a, D, DFF, 2, r}; r -= I_GU;
;         return TrD{P.w2d, P.W2D, nullptr, DFF, D, 0, r};
;     }, gw, NITEMS, NGW, lane, scr);
; __global__ void __launch_bounds__(NTHR, 2) mk_fwd(Args a) {
;     ...
;     {
;         constexpr int NU1 = (M / 256) * (2 * DFF / 256);
;         const int rounds = (NU1 + G - 1) / G, idle0 = NU1 - (rounds - 1) * G;
;         if (idle0 >= G) p0_deferred(P, lds, gw, NGW, wave, lane);
;         else if ((int)blockIdx.x >= idle0) p0_deferred(P, lds, ((int)blockIdx.x - idle0) * NWAVES + wave, (G - idle0) * NWAVES, wave, lane);
.LBB0_106:
	s_lshl_b32 s0, s87, 9
	s_add_u32 s72, s90, 0xc00000
	s_addc_u32 s73, s91, 0
	v_writelane_b32 v254, s0, 41
	s_add_u32 s0, s90, 0x1800000
	s_addc_u32 s1, s91, 0
	v_writelane_b32 v254, s0, 42
	s_nop 1
	v_writelane_b32 v254, s1, 43
	s_add_u32 s0, s90, 0x2500000
	s_addc_u32 s1, s91, 0
	s_add_u32 s94, s90, 0x2b00000
	s_addc_u32 s95, s91, 0
	s_add_u32 s96, s90, 0x1200000
	v_writelane_b32 v254, s0, 44
	s_addc_u32 s97, s91, 0
	s_nop 0
	v_writelane_b32 v254, s1, 45
	s_add_u32 s0, s90, 0x1a00000
	s_addc_u32 s1, s91, 0
	v_writelane_b32 v254, s0, 46
	s_nop 1
	v_writelane_b32 v254, s1, 47
	s_abs_i32 s0, s87
	s_waitcnt vmcnt(4)
	v_cvt_f32_u32_e32 v2, s0
	s_add_i32 s1, s87, 0x5ab
	s_xor_b32 s2, s1, s87
	s_sub_i32 s3, 0, s0
	v_rcp_iflag_f32_e32 v2, v2
	s_ashr_i32 s29, s2, 31
	s_abs_i32 s1, s1
	v_mul_f32_e32 v2, 0x4f7ffffe, v2
	v_cvt_u32_f32_e32 v2, v2
	s_nop 0
	v_readfirstlane_b32 s2, v2
	s_mul_i32 s3, s3, s2
	s_mul_hi_u32 s3, s2, s3
	s_add_i32 s2, s2, s3
	s_mul_hi_u32 s2, s1, s2
	s_mul_i32 s3, s2, s0
	s_sub_i32 s1, s1, s3
	s_add_i32 s4, s2, 1
	s_sub_i32 s3, s1, s0
	s_cmp_ge_u32 s1, s0
	s_cselect_b32 s2, s4, s2
	s_cselect_b32 s1, s3, s1
	s_add_i32 s3, s2, 1
	s_cmp_ge_u32 s1, s0
	s_cselect_b32 s0, s3, s2
	s_xor_b32 s30, s0, s29
	s_sub_i32 s0, s30, s29
	v_writelane_b32 v254, s0, 48
	s_add_i32 s0, s0, -1
	s_mul_i32 s0, s0, s87
	v_writelane_b32 v254, s0, 49
	s_sub_i32 s0, 0x5ac, s0
	s_cmp_le_i32 s87, s0
	s_cselect_b64 s[2:3], -1, 0
	v_writelane_b32 v254, s2, 50
	s_cmp_gt_i32 s87, s0
	s_nop 0
	v_writelane_b32 v254, s3, 51
	v_writelane_b32 v254, s0, 52
	s_mov_b64 s[0:1], -1
	s_movk_i32 s99, 0x1e00
	s_movk_i32 s100, 0x1dff
	s_mov_b32 s98, 0
	s_cbranch_scc0 .Lp1_gen
	s_movk_i32 s98, 0xe00
.Lp1_gen:
	v_writelane_b32 v254, s30, 53
	v_writelane_b32 v254, s29, 55
	s_nop 0
	v_readlane_b32 s101, v254, 35
	s_add_i32 s0, s101, s98
	s_nop 3
	v_writelane_b32 v254, s0, 35
	s_nop 3
.Lp1_gen2:
	v_readlane_b32 s0, v254, 35
	s_cmp_gt_i32 s0, s100
	v_readlane_b32 s1, v254, 36
	s_cbranch_scc1 .LBB0_221
	v_readlane_b32 s30, v254, 35
	s_mov_b32 s46, 0
	s_mov_b64 s[4:5], 0
	s_cmpk_lt_i32 s30, 0x580
	s_movk_i32 s53, 0x400
	v_readlane_b32 s31, v254, 36
	s_cbranch_scc1 .LBB0_114
	s_cmpk_gt_u32 s30, 0xb7f
	s_cbranch_scc0 .LBB0_115
	s_cmpk_gt_u32 s30, 0xd7f
	s_cbranch_scc0 .LBB0_116
	s_cmpk_gt_u32 s30, 0x12ff
	s_cbranch_scc0 .LBB0_117
	s_cmpk_gt_u32 s30, 0x187f
	s_cbranch_scc0 .LBB0_118
	v_readlane_b32 s20, v254, 3
	v_readlane_b32 s26, v254, 9
	v_readlane_b32 s27, v254, 10
	s_add_i32 s47, s30, 0xffffe780
	s_mov_b64 s[0:1], 0
	v_readlane_b32 s21, v254, 4
	v_readlane_b32 s22, v254, 5
	v_readlane_b32 s23, v254, 6
	v_readlane_b32 s24, v254, 7
	v_readlane_b32 s25, v254, 8
	s_mov_b64 s[2:3], s[26:27]
	s_branch .LBB0_119

; #define LAS __attribute__((address_space(3)))
; __device__ __forceinline__ void tr_load(const TrD& d, int lane, f32x4 (&v)[8], float (&gg)[8]) {
;     const int nblk = d.N / 32, kb = d.item / nblk, nb = d.item % nblk, k0 = 64 * kb, n0 = 32 * nb;
;     const int row8 = lane >> 3, c4 = lane & 7;
; #pragma unroll
;     for (int i = 0; i < 8; ++i) v[i] = __builtin_nontemporal_load((const f32x4*)(d.W + (size_t)(k0 + 8 * i + row8) * d.N + n0 + 4 * c4));
; #pragma unroll
;     for (int i = 0; i < 8; ++i) { const float* gp = d.gk ? d.gk + k0 + 8 * i + row8 : d.W; const float x = __builtin_nontemporal_load(gp); gg[i] = d.gk ? x : 1.f; }
; }
; __device__ __forceinline__ void tr_finish(const TrD& d, int lane, const f32x4 (&v)[8], const float (&gg)[8], LAS float* scr) {
;     const int nblk = d.N / 32, kb = d.item / nblk, nb = d.item % nblk, k0 = 64 * kb, n0 = 32 * nb, K = d.K, mode = d.mode;
;     const int rbase = mode == 0 ? n0 : (256 * (n0 >> 7) + (n0 & 127) + (mode == 2 ? 128 : 0));
;     {
;         const int row8 = lane >> 3, c4 = lane & 7;
.LBB0_131:
	s_lshr_b32 s6, s57, 5
	v_cvt_f32_u32_e32 v2, s6
	v_readlane_b32 s7, v254, 34
	s_lshl_b32 s7, s7, 14
	s_add_i32 s28, s7, 0
	v_rcp_iflag_f32_e32 v2, v2
	s_sub_i32 s7, 0, s6
	s_abs_i32 s19, s47
	s_ashr_i32 s18, s47, 31
	v_mul_f32_e32 v2, 0x4f7ffffe, v2
	v_cvt_u32_f32_e32 v2, v2
	v_lshrrev_b32_e32 v66, 3, v162
	v_and_b32_e32 v34, 28, v163
	v_mov_b32_e32 v69, 0
	v_readfirstlane_b32 s20, v2
	s_mul_i32 s7, s7, s20
	s_mul_hi_u32 s7, s20, s7
	s_add_i32 s20, s20, s7
	s_mul_hi_u32 s7, s19, s20
	s_mul_i32 s20, s7, s6
	s_sub_i32 s19, s19, s20
	s_add_i32 s21, s7, 1
	s_sub_i32 s20, s19, s6
	s_cmp_ge_u32 s19, s6
	s_cselect_b32 s7, s21, s7
	s_cselect_b32 s19, s20, s19
	s_add_i32 s20, s7, 1
	s_cmp_ge_u32 s19, s6
	s_cselect_b32 s7, s20, s7
	s_xor_b32 s7, s7, s18
	s_sub_i32 s7, s7, s18
	s_mul_i32 s18, s7, s6
	s_lshl_b32 s6, s7, 6
	s_sub_i32 s7, s47, s18
	v_or_b32_e32 v16, s6, v66
	s_lshl_b32 s18, s7, 5
	s_ashr_i32 s7, s6, 31
	v_or_b32_e32 v14, 48, v16
	s_mul_i32 s22, s7, s57
	v_mad_u64_u32 v[14:15], s[20:21], v14, s57, 0
	s_ashr_i32 s19, s18, 31
	v_add_u32_e32 v15, s22, v15
	s_lshl_b64 s[18:19], s[18:19], 2
	v_lshl_add_u64 v[14:15], v[14:15], 2, s[2:3]
	v_lshlrev_b32_e32 v68, 2, v34
	v_lshl_add_u64 v[14:15], v[14:15], 0, s[18:19]
	v_or_b32_e32 v4, 8, v16
	v_or_b32_e32 v6, 16, v16
	v_or_b32_e32 v8, 24, v16
	v_or_b32_e32 v10, 32, v16
	v_or_b32_e32 v12, 40, v16
	v_lshl_add_u64 v[36:37], v[14:15], 0, v[68:69]
	v_or_b32_e32 v14, 56, v16
	v_mad_u64_u32 v[2:3], s[20:21], v16, s57, 0
	v_mad_u64_u32 v[4:5], s[20:21], v4, s57, 0
	v_mad_u64_u32 v[6:7], s[20:21], v6, s57, 0
	v_mad_u64_u32 v[8:9], s[20:21], v8, s57, 0
	v_mad_u64_u32 v[10:11], s[20:21], v10, s57, 0
	v_mad_u64_u32 v[12:13], s[20:21], v12, s57, 0
	v_mad_u64_u32 v[14:15], s[20:21], v14, s57, 0
	v_add_u32_e32 v3, s22, v3
	v_add_u32_e32 v5, s22, v5
	v_add_u32_e32 v7, s22, v7
	v_add_u32_e32 v9, s22, v9
	v_add_u32_e32 v11, s22, v11
	v_add_u32_e32 v13, s22, v13
	v_add_u32_e32 v15, s22, v15
	s_cmp_eq_u64 s[4:5], 0
	v_lshl_add_u64 v[2:3], v[2:3], 2, s[2:3]
	v_lshl_add_u64 v[4:5], v[4:5], 2, s[2:3]
	v_lshl_add_u64 v[6:7], v[6:7], 2, s[2:3]
	v_lshl_add_u64 v[8:9], v[8:9], 2, s[2:3]
	v_lshl_add_u64 v[10:11], v[10:11], 2, s[2:3]
	v_lshl_add_u64 v[12:13], v[12:13], 2, s[2:3]
	v_lshl_add_u64 v[14:15], v[14:15], 2, s[2:3]
	s_cselect_b64 vcc, -1, 0
	s_lshl_b64 s[6:7], s[6:7], 2
	v_lshl_add_u64 v[2:3], v[2:3], 0, s[18:19]
	v_lshl_add_u64 v[4:5], v[4:5], 0, s[18:19]
	v_lshl_add_u64 v[6:7], v[6:7], 0, s[18:19]
	v_lshl_add_u64 v[8:9], v[8:9], 0, s[18:19]
	v_lshl_add_u64 v[10:11], v[10:11], 0, s[18:19]
	v_lshl_add_u64 v[12:13], v[12:13], 0, s[18:19]
	v_lshl_add_u64 v[14:15], v[14:15], 0, s[18:19]
	s_add_u32 s4, s4, s6
	v_lshl_add_u64 v[2:3], v[2:3], 0, v[68:69]
	v_lshl_add_u64 v[4:5], v[4:5], 0, v[68:69]
	v_lshl_add_u64 v[6:7], v[6:7], 0, v[68:69]
	v_lshl_add_u64 v[8:9], v[8:9], 0, v[68:69]
	v_lshl_add_u64 v[10:11], v[10:11], 0, v[68:69]
	v_lshl_add_u64 v[12:13], v[12:13], 0, v[68:69]
	v_lshl_add_u64 v[38:39], v[14:15], 0, v[68:69]
	s_addc_u32 s5, s5, s7
	v_lshlrev_b32_e32 v68, 2, v66
	v_mov_b32_e32 v18, s3
	v_lshl_add_u64 v[14:15], s[4:5], 0, v[68:69]
	v_mov_b32_e32 v19, s2
	v_cndmask_b32_e32 v17, v15, v18, vcc
	v_cndmask_b32_e32 v16, v14, v19, vcc
	global_load_dword v35, v[16:17], off nt
	v_lshl_add_u64 v[16:17], v[14:15], 0, 32
	v_cndmask_b32_e32 v17, v17, v18, vcc
	v_cndmask_b32_e32 v16, v16, v19, vcc
	global_load_dword v40, v[16:17], off nt
	v_lshl_add_u64 v[16:17], v[14:15], 0, 64
	v_cndmask_b32_e32 v17, v17, v18, vcc
	v_cndmask_b32_e32 v16, v16, v19, vcc
	s_mov_b64 s[24:25], 0x60
	global_load_dword v41, v[16:17], off nt
	v_lshl_add_u64 v[16:17], v[14:15], 0, s[24:25]
	v_cndmask_b32_e32 v17, v17, v18, vcc
	v_cndmask_b32_e32 v16, v16, v19, vcc
	s_mov_b64 s[66:67], 0x80
	global_load_dword v42, v[16:17], off nt
	v_lshl_add_u64 v[16:17], v[14:15], 0, s[66:67]
	v_cndmask_b32_e32 v17, v17, v18, vcc
	v_cndmask_b32_e32 v16, v16, v19, vcc
	s_mov_b64 s[50:51], 0xa0
	global_load_dword v43, v[16:17], off nt
	v_lshl_add_u64 v[16:17], v[14:15], 0, s[50:51]
	v_cndmask_b32_e32 v17, v17, v18, vcc
	v_cndmask_b32_e32 v16, v16, v19, vcc
	s_mov_b64 s[48:49], 0xc0
	global_load_dword v44, v[16:17], off nt
	v_lshl_add_u64 v[16:17], v[14:15], 0, s[48:49]
	v_cndmask_b32_e32 v17, v17, v18, vcc
	v_cndmask_b32_e32 v16, v16, v19, vcc
	global_load_dword v45, v[16:17], off nt
	s_mov_b64 s[74:75], 0xe0
	v_lshl_add_u64 v[14:15], v[14:15], 0, s[74:75]
	v_cndmask_b32_e32 v15, v15, v18, vcc
	v_cndmask_b32_e32 v14, v14, v19, vcc
	global_load_dword v46, v[14:15], off nt
	global_load_dwordx4 v[26:29], v[2:3], off nt
	global_load_dwordx4 v[30:33], v[4:5], off nt
	global_load_dwordx4 v[22:25], v[6:7], off nt
	global_load_dwordx4 v[18:21], v[8:9], off nt
	s_nop 0
	global_load_dwordx4 v[14:17], v[10:11], off nt
	s_nop 0
	global_load_dwordx4 v[10:13], v[12:13], off nt
	s_nop 0
	global_load_dwordx4 v[6:9], v[36:37], off nt
	global_load_dwordx4 v[2:5], v[38:39], off nt
	v_lshrrev_b32_e32 v39, 2, v162
	v_mul_u32_u24_e32 v37, 0x84, v66
	v_lshlrev_b32_e32 v36, 3, v1
	v_mul_u32_u24_e32 v38, 0x420, v1
	v_and_b32_e32 v79, 8, v39
	v_or_b32_e32 v67, 8, v66
	v_or_b32_e32 v75, 16, v66
	v_or_b32_e32 v77, 24, v66
	v_add3_u32 v81, s28, v38, v68
	v_or_b32_e32 v83, 4, v79
	s_lshl_b32 s68, s69, 1
	v_lshlrev_b32_e32 v68, 2, v34
	s_movk_i32 s52, 0x3ff
	s_movk_i32 s54, 0x7fff
	s_mov_b32 s55, 0xffff0000
	v_lshlrev_b32_e32 v70, 1, v36
	v_mov_b32_e32 v87, 0x7c3
	s_mov_b32 s60, s30
	s_waitcnt vmcnt(15)
	v_cndmask_b32_e64 v88, v35, 1.0, vcc
	v_lshl_add_u32 v35, v1, 4, s28
	v_add_u32_e32 v85, v35, v37
	s_waitcnt vmcnt(14)
	v_cndmask_b32_e64 v86, v40, 1.0, vcc
	s_waitcnt vmcnt(13)
	v_cndmask_b32_e64 v84, v41, 1.0, vcc
	s_waitcnt vmcnt(12)
	v_cndmask_b32_e64 v82, v42, 1.0, vcc
	s_waitcnt vmcnt(11)
	v_cndmask_b32_e64 v80, v43, 1.0, vcc
	s_waitcnt vmcnt(10)
	v_cndmask_b32_e64 v78, v44, 1.0, vcc
	s_waitcnt vmcnt(8)
	v_cndmask_b32_e64 v74, v46, 1.0, vcc
	v_cndmask_b32_e64 v76, v45, 1.0, vcc
	s_branch .LBB0_134
; #define GAS __attribute__((address_space(1)))
; #define LAS __attribute__((address_space(3)))
; #define LDS_WAIT() asm volatile("s_waitcnt lgkmcnt(0)" ::: "memory")
; __device__ __forceinline__ unsigned pk2(float lo, float hi) { return f2bf(lo) | (f2bf(hi) << 16); }
; __device__ __forceinline__ void tr_finish(const TrD& d, int lane, const f32x4 (&v)[8], const float (&gg)[8], LAS float* scr) {
;     ...
;         for (int i = 0; i < 8; ++i) { LAS float* dd = scr + (8 * i + row8) * 33 + 4 * c4; dd[0] = v[i][0] * gg[i]; dd[1] = v[i][1] * gg[i]; dd[2] = v[i][2] * gg[i]; dd[3] = v[i][3] * gg[i]; }
;     }
;     LDS_WAIT(); asm volatile("" ::: "memory");
;     const int c = lane & 7;
; #pragma unroll
;     for (int j = 0; j < 4; ++j) { const int n = (lane >> 3) + 8 * j; const LAS float* sp = scr + (8 * c) * 33 + n;
;         v4u o; o.x = pk2(sp[0 * 33], sp[1 * 33]); o.y = pk2(sp[2 * 33], sp[3 * 33]); o.z = pk2(sp[4 * 33], sp[5 * 33]); o.w = pk2(sp[6 * 33], sp[7 * 33]);
;         const int orow = mode == 3 ? win_perm(n0 + n) : rbase + n;
;         *(GAS v4u*)(d.WT + (size_t)orow * K + k0 + 8 * c) = o; }
;     LDS_WAIT(); asm volatile("" ::: "memory");
; }
; template <class DescFn>
; __device__ __forceinline__ void tr_loop(DescFn desc, int first, int nitems, int stride, int lane, LAS float* scr) {
;     ...
;         { const int itn = it + stride; const bool more = itn < nitems; d1 = desc(more ? itn : it); tr_load(d1, lane, v1, g1); __builtin_amdgcn_sched_barrier(0); tr_finish(d0, lane, v0, g0, scr); if (!more) break; it = itn; }
;         { const int itn = it + stride; const bool more = itn < nitems; d0 = desc(more ? itn : it); tr_load(d0, lane, v0, g0); __builtin_amdgcn_sched_barrier(0); tr_finish(d1, lane, v1, g1, scr); if (!more) break; it = itn; }
.LBB0_132:
	s_waitcnt lgkmcnt(3)
	v_bfe_u32 v43, v41, 16, 1
	v_add3_u32 v41, v41, v43, s54
	v_bfe_u32 v43, v40, 16, 1
	v_add3_u32 v40, v40, v43, s54
	v_lshrrev_b32_e32 v40, 16, v40
	v_and_or_b32 v44, v41, s55, v40
	s_waitcnt lgkmcnt(2)
	v_bfe_u32 v40, v39, 16, 1
	v_add3_u32 v39, v39, v40, s54
	v_bfe_u32 v40, v38, 16, 1
	v_add3_u32 v38, v38, v40, s54
	v_lshrrev_b32_e32 v38, 16, v38
	v_and_or_b32 v45, v39, s55, v38
	s_waitcnt lgkmcnt(1)
	v_bfe_u32 v38, v37, 16, 1
	v_add3_u32 v37, v37, v38, s54
	v_bfe_u32 v38, v36, 16, 1
	v_add3_u32 v36, v36, v38, s54
	v_lshrrev_b32_e32 v36, 16, v36
	v_and_or_b32 v46, v37, s55, v36
	s_waitcnt lgkmcnt(0)
	v_bfe_u32 v36, v35, 16, 1
	v_add3_u32 v35, v35, v36, s54
	v_bfe_u32 v36, v34, 16, 1
	v_add3_u32 v34, v34, v36, s54
	v_lshrrev_b32_e32 v34, 16, v34
	v_and_or_b32 v47, v35, s55, v34
	v_ashrrev_i32_e32 v34, 31, v42
	s_waitcnt vmcnt(11)
	v_cndmask_b32_e64 v88, v72, 1.0, s[2:3]
	s_waitcnt vmcnt(10)
	v_cndmask_b32_e64 v86, v73, 1.0, s[2:3]
	s_waitcnt vmcnt(9)
	v_cndmask_b32_e64 v84, v103, 1.0, s[2:3]
	s_waitcnt vmcnt(8)
	v_cndmask_b32_e64 v82, v104, 1.0, s[2:3]
	s_waitcnt vmcnt(7)
	v_cndmask_b32_e64 v80, v105, 1.0, s[2:3]
	s_waitcnt vmcnt(5)
	v_cndmask_b32_e64 v78, v106, 1.0, s[2:3]
	s_waitcnt vmcnt(4)
	v_cndmask_b32_e64 v76, v107, 1.0, s[2:3]
	s_waitcnt vmcnt(3)
	v_cndmask_b32_e64 v74, v108, 1.0, s[2:3]
	v_mul_lo_u32 v36, s29, v42
	v_mul_lo_u32 v37, s28, v34
	v_mad_u64_u32 v[34:35], s[2:3], s28, v42, 0
	v_add3_u32 v35, v35, v37, v36
	v_lshl_add_u64 v[34:35], v[34:35], 1, s[30:31]
	v_lshl_add_u64 v[34:35], s[34:35], 1, v[34:35]
	v_mov_b32_e32 v71, v69
	v_lshl_add_u64 v[34:35], v[34:35], 0, v[70:71]
	global_store_dwordx4 v[34:35], v[44:47], off
	s_waitcnt lgkmcnt(0)
	s_add_i32 s60, s56, s69
	s_cmp_gt_i32 s60, s100
	s_cselect_b64 s[4:5], -1, 0

; template <class DescFn>
; __device__ __forceinline__ void tr_loop(DescFn desc, int first, int nitems, int stride, int lane, LAS float* scr) {
;     ...
;         { const int itn = it + stride; const bool more = itn < nitems; d1 = desc(more ? itn : it); tr_load(d1, lane, v1, g1); __builtin_amdgcn_sched_barrier(0); tr_finish(d0, lane, v0, g0, scr); if (!more) break; it = itn; }
;         { const int itn = it + stride; const bool more = itn < nitems; d0 = desc(more ? itn : it); tr_load(d0, lane, v0, g0); __builtin_amdgcn_sched_barrier(0); tr_finish(d1, lane, v1, g1, scr); if (!more) break; it = itn; }
; __device__ __forceinline__ void p0_deferred(const Ptrs& P, LAS unsigned char* lds, int gw, int NGW, int wave, int lane) {
;     ...
;     tr_loop([&](int it) {
;         int r = it;
;         if (r < I_D) return TrD{P.w1d, P.W1D, nullptr, DFF, D, 0, r}; r -= I_D;
;         if (r < I_IN) return TrD{P.win, P.WIN, P.gma, D, INW, 3, r}; r -= I_IN;
;         if (r < I_OUT) return TrD{P.wout, P.WOUT, nullptr, D, D, 0, r}; r -= I_OUT;
;         if (r < I_GU) return TrD{P.w2g, P.W2GU, P.g2a, D, DFF, 1, r}; r -= I_GU;
;         if (r < I_GU) return TrD{P.w2u, P.W2GU, P.g2a, D, DFF, 2, r}; r -= I_GU;
;         return TrD{P.w2d, P.W2D, nullptr, DFF, D, 0, r};
;     }, gw, NITEMS, NGW, lane, scr);
.LBB0_134:
	s_add_i32 s56, s60, s69
	s_cmp_lt_i32 s56, s99
	s_cselect_b64 s[40:41], -1, 0
	s_and_b64 s[2:3], s[40:41], exec
	s_cselect_b32 s35, s56, s60
	s_cmpk_lt_i32 s35, 0x580
	s_mov_b64 s[6:7], -1
	s_cbranch_scc1 .LBB0_141
	s_cmpk_gt_u32 s35, 0xb7f
	s_cbranch_scc0 .LBB0_142
	s_cmpk_gt_u32 s35, 0xd7f
	s_cbranch_scc0 .LBB0_143
	s_cmpk_gt_u32 s35, 0x12ff
	s_cbranch_scc0 .LBB0_144
	s_cmpk_gt_u32 s35, 0x187f
	s_mov_b64 s[38:39], -1
	s_cbranch_scc0 .LBB0_186
	v_readlane_b32 s20, v254, 3
	v_readlane_b32 s26, v254, 9
	v_readlane_b32 s27, v254, 10
	s_add_i32 s34, s35, 0xffffe780
	s_mov_b64 s[44:45], 0
	v_readlane_b32 s21, v254, 4
	v_readlane_b32 s22, v254, 5
	v_readlane_b32 s23, v254, 6
	v_readlane_b32 s24, v254, 7
	v_readlane_b32 s25, v254, 8
	s_mov_b64 s[4:5], s[26:27]
	s_cbranch_execz .LBB0_187
	v_readlane_b32 s30, v254, 44
	s_movk_i32 s61, 0x400
	s_mov_b64 s[28:29], 0xb00
	s_mov_b32 s58, 0
	v_readlane_b32 s31, v254, 45
	s_cbranch_execz .LBB0_145
	s_branch .LBB0_146

; #define GAS __attribute__((address_space(1)))
; #define LAS __attribute__((address_space(3)))
; #define LDS_WAIT() asm volatile("s_waitcnt lgkmcnt(0)" ::: "memory")
; __device__ __forceinline__ unsigned pk2(float lo, float hi) { return f2bf(lo) | (f2bf(hi) << 16); }
; __device__ __forceinline__ void tr_finish(const TrD& d, int lane, const f32x4 (&v)[8], const float (&gg)[8], LAS float* scr) {
;     ...
;         for (int i = 0; i < 8; ++i) { LAS float* dd = scr + (8 * i + row8) * 33 + 4 * c4; dd[0] = v[i][0] * gg[i]; dd[1] = v[i][1] * gg[i]; dd[2] = v[i][2] * gg[i]; dd[3] = v[i][3] * gg[i]; }
;     }
;     LDS_WAIT(); asm volatile("" ::: "memory");
;     const int c = lane & 7;
; #pragma unroll
;     for (int j = 0; j < 4; ++j) { const int n = (lane >> 3) + 8 * j; const LAS float* sp = scr + (8 * c) * 33 + n;
;         v4u o; o.x = pk2(sp[0 * 33], sp[1 * 33]); o.y = pk2(sp[2 * 33], sp[3 * 33]); o.z = pk2(sp[4 * 33], sp[5 * 33]); o.w = pk2(sp[6 * 33], sp[7 * 33]);
;         const int orow = mode == 3 ? win_perm(n0 + n) : rbase + n;
;         *(GAS v4u*)(d.WT + (size_t)orow * K + k0 + 8 * c) = o; }
;     LDS_WAIT(); asm volatile("" ::: "memory");
; }
; template <class DescFn>
; __device__ __forceinline__ void tr_loop(DescFn desc, int first, int nitems, int stride, int lane, LAS float* scr) {
;     ...
;         { const int itn = it + stride; const bool more = itn < nitems; d1 = desc(more ? itn : it); tr_load(d1, lane, v1, g1); __builtin_amdgcn_sched_barrier(0); tr_finish(d0, lane, v0, g0, scr); if (!more) break; it = itn; }
;         { const int itn = it + stride; const bool more = itn < nitems; d0 = desc(more ? itn : it); tr_load(d0, lane, v0, g0); __builtin_amdgcn_sched_barrier(0); tr_finish(d1, lane, v1, g1, scr); if (!more) break; it = itn; }
.LBB0_175:
	s_waitcnt lgkmcnt(3)
	v_bfe_u32 v11, v9, 16, 1
	v_add3_u32 v9, v9, v11, s54
	v_bfe_u32 v11, v8, 16, 1
	v_add3_u32 v8, v8, v11, s54
	v_lshrrev_b32_e32 v8, 16, v8
	v_and_or_b32 v12, v9, s55, v8
	s_waitcnt lgkmcnt(2)
	v_bfe_u32 v8, v7, 16, 1
	v_add3_u32 v7, v7, v8, s54
	v_bfe_u32 v8, v6, 16, 1
	v_add3_u32 v6, v6, v8, s54
	v_lshrrev_b32_e32 v6, 16, v6
	v_and_or_b32 v13, v7, s55, v6
	s_waitcnt lgkmcnt(1)
	v_bfe_u32 v6, v5, 16, 1
	v_add3_u32 v5, v5, v6, s54
	v_bfe_u32 v6, v4, 16, 1
	v_add3_u32 v4, v4, v6, s54
	v_lshrrev_b32_e32 v4, 16, v4
	v_and_or_b32 v14, v5, s55, v4
	s_waitcnt lgkmcnt(0)
	v_bfe_u32 v4, v3, 16, 1
	v_add3_u32 v3, v3, v4, s54
	v_bfe_u32 v4, v2, 16, 1
	v_add3_u32 v2, v2, v4, s54
	v_lshrrev_b32_e32 v2, 16, v2
	v_and_or_b32 v15, v3, s55, v2
	v_ashrrev_i32_e32 v2, 31, v10
	v_mul_lo_u32 v4, s1, v10
	v_mul_lo_u32 v5, s0, v2
	v_mad_u64_u32 v[2:3], s[0:1], s0, v10, 0
	v_add3_u32 v3, v3, v5, v4
	v_lshl_add_u64 v[2:3], v[2:3], 1, s[70:71]
	v_lshl_add_u64 v[2:3], s[44:45], 1, v[2:3]
	v_mov_b32_e32 v71, v69
	v_lshl_add_u64 v[2:3], v[2:3], 0, v[70:71]
	global_store_dwordx4 v[2:3], v[12:15], off
	s_waitcnt lgkmcnt(0)
	s_andn2_b64 vcc, exec, s[40:41]
	s_mov_b64 s[4:5], -1
	s_cbranch_vccnz .LBB0_133
	s_xor_b64 s[40:41], s[42:43], -1
	s_add_i32 s0, s68, s60
	s_cmp_lt_i32 s0, s99
	s_cselect_b32 s47, s0, s56
	s_cmpk_lt_i32 s47, 0x580
	s_cbranch_scc1 .LBB0_183
	s_cmpk_gt_u32 s47, 0xb7f
	s_cbranch_scc0 .LBB0_184
	s_cmpk_gt_u32 s47, 0xd7f
	s_cbranch_scc0 .LBB0_185
	s_cmpk_gt_u32 s47, 0x12ff
	s_cbranch_scc0 .LBB0_188
	s_cmpk_gt_u32 s47, 0x187f
	s_cbranch_scc0 .LBB0_219
	v_readlane_b32 s20, v254, 3
	v_readlane_b32 s26, v254, 9
	v_readlane_b32 s27, v254, 10
	s_add_i32 s37, s47, 0xffffe780
	s_mov_b64 s[6:7], 0
	v_readlane_b32 s21, v254, 4
	v_readlane_b32 s22, v254, 5
	v_readlane_b32 s23, v254, 6
	v_readlane_b32 s24, v254, 7
	v_readlane_b32 s25, v254, 8
	s_mov_b64 s[4:5], s[26:27]
	s_cbranch_execz .LBB0_220
	v_readlane_b32 s70, v254, 44
	s_movk_i32 s57, 0x400
	s_mov_b64 s[0:1], 0xb00
	s_mov_b32 s46, 0
	v_readlane_b32 s71, v254, 45
	s_cbranch_execz .LBB0_189
	s_branch .LBB0_190

; #define LAS __attribute__((address_space(3)))
; __device__ __forceinline__ void p0_deferred(const Ptrs& P, LAS unsigned char* lds, int gw, int NGW, int wave, int lane) {
;     ...
;     {
;         LAS float* fl = (LAS float*)(lds + 12288);
;         if (threadIdx.x < 40) fl[threadIdx.x] = INVF[threadIdx.x];
;         __syncthreads();
.LBB0_221:
	s_nop 3
	v_writelane_b32 v254, s101, 35
	s_nop 3
	s_cmp_eq_u32 s98, 1
	s_cbranch_scc1 .Lp1_done2
	v_cmp_gt_u32_e32 vcc, 40, v0
	s_and_saveexec_b64 s[0:1], vcc
	s_cbranch_execz .LBB0_223
	s_getpc_b64 s[2:3]
	s_add_u32 s2, s2, INVF@rel32@lo+4
	s_addc_u32 s3, s3, INVF@rel32@hi+12
	global_load_dword v2, v163, s[2:3]
	v_add_u32_e32 v3, 0, v163
	s_waitcnt vmcnt(0)
	ds_write_b32 v3, v2 offset:12288

; __device__ __forceinline__ void p0_deferred(const Ptrs& P, LAS unsigned char* lds, int gw, int NGW, int wave, int lane) {
;     ...
;     tr_loop([&](int it) {
;         int r = it;
;         if (r < I_D) return TrD{P.w1d, P.W1D, nullptr, DFF, D, 0, r}; r -= I_D;
;         if (r < I_IN) return TrD{P.win, P.WIN, P.gma, D, INW, 3, r}; r -= I_IN;
;         if (r < I_OUT) return TrD{P.wout, P.WOUT, nullptr, D, D, 0, r}; r -= I_OUT;
;         if (r < I_GU) return TrD{P.w2g, P.W2GU, P.g2a, D, DFF, 1, r}; r -= I_GU;
;         if (r < I_GU) return TrD{P.w2u, P.W2GU, P.g2a, D, DFF, 2, r}; r -= I_GU;
;         return TrD{P.w2d, P.W2D, nullptr, DFF, D, 0, r};
;     }, gw, NITEMS, NGW, lane, scr);
; __global__ void __launch_bounds__(NTHR, 2) mk_fwd(Args a) {
;     ...
;         if (idle0 >= G) p0_deferred(P, lds, gw, NGW, wave, lane);
;         else if ((int)blockIdx.x >= idle0) p0_deferred(P, lds, ((int)blockIdx.x - idle0) * NWAVES + wave, (G - idle0) * NWAVES, wave, lane);
.LBB0_226:
	s_or_b64 exec, exec, s[0:1]
	s_cmp_eq_u32 s98, 0
	s_cbranch_scc1 .LBB0_349
	v_readlane_b32 s0, v254, 52
	s_cmp_lt_i32 s86, s0
	s_cbranch_scc1 .LBB0_349
	s_sub_i32 s1, s86, s0
	s_lshl_b32 s1, s1, 3
	v_readlane_b32 s2, v254, 34
	s_add_i32 s1, s1, s2
	s_sub_i32 s0, s87, s0
	s_lshl_b32 s69, s0, 3
	s_movk_i32 s99, 0xe00
	s_movk_i32 s100, 0xdff
	s_mov_b32 s98, 1
	s_nop 3
	v_writelane_b32 v254, s1, 35
	s_nop 3
	s_branch .Lp1_gen2
.Lp1_done2:
	v_readlane_b32 s0, v254, 12
	s_lshl_b32 s69, s0, 3
	v_readlane_b32 s29, v254, 55
	v_readlane_b32 s30, v254, 53
